# scan2 carry-in fold: aggregate loads issued in batches of 8/4/2/1 instead of one dependent round trip per earlier panel (same fold order, bit-identical)
# baseline (speedup 1.0000x reference)
; __device__ __forceinline__ void scan_pass2_tile(const unsigned* au, const f32x4* saggP, const f32x4* saggH, const f32x4* cpreP, const f32x4* cpreH, const bf16_t* gate, bf16_t* y, int pm, int blk, int tid) {
;     const int cl = tid >> 6, ql = tid & 63, b = pm / SCAN_NSC, c4 = blk * 64 + ql, ck = pm * SCAN_SC + cl;
;     f32x4 C = {0.f, 0.f, 0.f, 0.f};
;     for (int j = b * SCAN_NSC; j < pm; ++j) { const f32x4 p = saggP[(size_t)j * 256 + c4], h = saggH[(size_t)j * 256 + c4]; C = p * C + h; }
;     f32x4 Hh = cpreP[(size_t)ck * 256 + c4] * C + cpreH[(size_t)ck * 256 + c4];
.LBB0_343:
	s_ashr_i32 s4, s64, 31
	s_ashr_i32 s66, s64, 2
	s_lshr_b32 s4, s4, 27
	s_add_i32 s4, s66, s4
	s_bfe_u32 s65, s30, 0x20006
	s_andn2_b32 s4, s4, 31
	v_mbcnt_lo_u32_b32 v5, -1, 0
	v_mbcnt_hi_u32_b32 v5, -1, v5
	s_cmp_ge_i32 s4, s66
	v_and_b32_e32 v4, 63, v5
	v_mov_b32_e32 v9, 0
	v_mov_b32_e32 v8, 0
	v_mov_b32_e32 v7, 0
	v_mov_b32_e32 v6, 0
	s_cbranch_scc1 .LBB0_346
	s_ashr_i32 s5, s4, 31
	s_lshl_b64 s[68:69], s[4:5], 12
	v_lshlrev_b32_e32 v0, 4, v4
	s_add_u32 s68, s22, s68
	v_lshl_or_b32 v0, s65, 10, v0
	s_addc_u32 s69, s23, s69
	v_mov_b32_e32 v6, 0
	v_mov_b32_e32 v7, v6
	v_mov_b32_e32 v8, v6
	v_mov_b32_e32 v9, v6
	s_add_u32 s98, s68, 0x80000
	s_addc_u32 s99, s69, 0
	s_sub_i32 s5, s66, s4
	v_add_u32_e32 v2, 0x1000, v0
	v_add_u32_e32 v3, 0x2000, v0
	v_add_u32_e32 v74, 0x3000, v0
	v_add_u32_e32 v75, 0x4000, v0
	v_add_u32_e32 v76, 0x5000, v0
	v_add_u32_e32 v77, 0x6000, v0
	v_add_u32_e32 v78, 0x7000, v0
.Lcarry_loop8:
	s_cmp_lt_u32 s5, 8
	s_cbranch_scc1 .Lcarry_tail4
	global_load_dwordx4 v[10:13], v0, s[68:69]
	global_load_dwordx4 v[14:17], v0, s[98:99]
	global_load_dwordx4 v[18:21], v2, s[68:69]
	global_load_dwordx4 v[22:25], v2, s[98:99]
	global_load_dwordx4 v[26:29], v3, s[68:69]
	global_load_dwordx4 v[30:33], v3, s[98:99]
	global_load_dwordx4 v[34:37], v74, s[68:69]
	global_load_dwordx4 v[38:41], v74, s[98:99]
	global_load_dwordx4 v[42:45], v75, s[68:69]
	global_load_dwordx4 v[46:49], v75, s[98:99]
	global_load_dwordx4 v[50:53], v76, s[68:69]
	global_load_dwordx4 v[54:57], v76, s[98:99]
	global_load_dwordx4 v[58:61], v77, s[68:69]
	global_load_dwordx4 v[62:65], v77, s[98:99]
	global_load_dwordx4 v[66:69], v78, s[68:69]
	global_load_dwordx4 v[70:73], v78, s[98:99]
	s_add_u32 s68, s68, 0x8000
	s_addc_u32 s69, s69, 0
	s_add_u32 s98, s98, 0x8000
	s_addc_u32 s99, s99, 0
	s_waitcnt vmcnt(14)
	v_pk_fma_f32 v[8:9], v[8:9], v[12:13], v[16:17]
	v_pk_fma_f32 v[6:7], v[6:7], v[10:11], v[14:15]
	s_waitcnt vmcnt(12)
	v_pk_fma_f32 v[8:9], v[8:9], v[20:21], v[24:25]
	v_pk_fma_f32 v[6:7], v[6:7], v[18:19], v[22:23]
	s_waitcnt vmcnt(10)
	v_pk_fma_f32 v[8:9], v[8:9], v[28:29], v[32:33]
	v_pk_fma_f32 v[6:7], v[6:7], v[26:27], v[30:31]
	s_waitcnt vmcnt(8)
	v_pk_fma_f32 v[8:9], v[8:9], v[36:37], v[40:41]
	v_pk_fma_f32 v[6:7], v[6:7], v[34:35], v[38:39]
	s_waitcnt vmcnt(6)
	v_pk_fma_f32 v[8:9], v[8:9], v[44:45], v[48:49]
	v_pk_fma_f32 v[6:7], v[6:7], v[42:43], v[46:47]
	s_waitcnt vmcnt(4)
	v_pk_fma_f32 v[8:9], v[8:9], v[52:53], v[56:57]
	v_pk_fma_f32 v[6:7], v[6:7], v[50:51], v[54:55]
	s_waitcnt vmcnt(2)
	v_pk_fma_f32 v[8:9], v[8:9], v[60:61], v[64:65]
	v_pk_fma_f32 v[6:7], v[6:7], v[58:59], v[62:63]
	s_waitcnt vmcnt(0)
	v_pk_fma_f32 v[8:9], v[8:9], v[68:69], v[72:73]
	v_pk_fma_f32 v[6:7], v[6:7], v[66:67], v[70:71]
	s_sub_u32 s5, s5, 8
	s_branch .Lcarry_loop8
.Lcarry_tail4:
	s_bitcmp1_b32 s5, 2
	s_cbranch_scc0 .Lcarry_tail2
	global_load_dwordx4 v[10:13], v0, s[68:69]
	global_load_dwordx4 v[14:17], v0, s[98:99]
	global_load_dwordx4 v[18:21], v2, s[68:69]
	global_load_dwordx4 v[22:25], v2, s[98:99]
	global_load_dwordx4 v[26:29], v3, s[68:69]
	global_load_dwordx4 v[30:33], v3, s[98:99]
	global_load_dwordx4 v[34:37], v74, s[68:69]
	global_load_dwordx4 v[38:41], v74, s[98:99]
	s_add_u32 s68, s68, 0x4000
	s_addc_u32 s69, s69, 0
	s_add_u32 s98, s98, 0x4000
	s_addc_u32 s99, s99, 0
	s_waitcnt vmcnt(6)
	v_pk_fma_f32 v[8:9], v[8:9], v[12:13], v[16:17]
	v_pk_fma_f32 v[6:7], v[6:7], v[10:11], v[14:15]
	s_waitcnt vmcnt(4)
	v_pk_fma_f32 v[8:9], v[8:9], v[20:21], v[24:25]
	v_pk_fma_f32 v[6:7], v[6:7], v[18:19], v[22:23]
	s_waitcnt vmcnt(2)
	v_pk_fma_f32 v[8:9], v[8:9], v[28:29], v[32:33]
	v_pk_fma_f32 v[6:7], v[6:7], v[26:27], v[30:31]
	s_waitcnt vmcnt(0)
	v_pk_fma_f32 v[8:9], v[8:9], v[36:37], v[40:41]
	v_pk_fma_f32 v[6:7], v[6:7], v[34:35], v[38:39]
.Lcarry_tail2:
	s_bitcmp1_b32 s5, 1
	s_cbranch_scc0 .Lcarry_tail1
	global_load_dwordx4 v[10:13], v0, s[68:69]
	global_load_dwordx4 v[14:17], v0, s[98:99]
	global_load_dwordx4 v[18:21], v2, s[68:69]
	global_load_dwordx4 v[22:25], v2, s[98:99]
	s_add_u32 s68, s68, 0x2000
	s_addc_u32 s69, s69, 0
	s_add_u32 s98, s98, 0x2000
	s_addc_u32 s99, s99, 0
	s_waitcnt vmcnt(2)
	v_pk_fma_f32 v[8:9], v[8:9], v[12:13], v[16:17]
	v_pk_fma_f32 v[6:7], v[6:7], v[10:11], v[14:15]
	s_waitcnt vmcnt(0)
	v_pk_fma_f32 v[8:9], v[8:9], v[20:21], v[24:25]
	v_pk_fma_f32 v[6:7], v[6:7], v[18:19], v[22:23]
.Lcarry_tail1:
	s_bitcmp1_b32 s5, 0
	s_cbranch_scc0 .LBB0_346
	global_load_dwordx4 v[10:13], v0, s[68:69]
	global_load_dwordx4 v[14:17], v0, s[98:99]
	s_add_u32 s68, s68, 0x1000
	s_addc_u32 s69, s69, 0
	s_add_u32 s98, s98, 0x1000
	s_addc_u32 s99, s99, 0
	s_waitcnt vmcnt(0)
	v_pk_fma_f32 v[8:9], v[8:9], v[12:13], v[16:17]
	v_pk_fma_f32 v[6:7], v[6:7], v[10:11], v[14:15]

; __global__ void __launch_bounds__(NTHREADS, 2) fwd_megakernel(Params p) {
	.amdhsa_kernel _Z14fwd_megakernel6Params
		.amdhsa_group_segment_fixed_size 0
		.amdhsa_private_segment_fixed_size 0
		.amdhsa_kernarg_size 416
		.amdhsa_user_sgpr_count 2
		.amdhsa_user_sgpr_dispatch_ptr 0
		.amdhsa_user_sgpr_queue_ptr 0
		.amdhsa_user_sgpr_kernarg_segment_ptr 1
		.amdhsa_user_sgpr_dispatch_id 0
		.amdhsa_user_sgpr_kernarg_preload_length 0
		.amdhsa_user_sgpr_kernarg_preload_offset 0
		.amdhsa_user_sgpr_private_segment_size 0
		.amdhsa_uses_dynamic_stack 0
		.amdhsa_enable_private_segment 0
		.amdhsa_system_sgpr_workgroup_id_x 1
		.amdhsa_system_sgpr_workgroup_id_y 0
		.amdhsa_system_sgpr_workgroup_id_z 0
		.amdhsa_system_sgpr_workgroup_info 0
		.amdhsa_system_vgpr_workitem_id 2
		.amdhsa_next_free_vgpr 251
		.amdhsa_next_free_sgpr 102
		.amdhsa_accum_offset 252
		.amdhsa_reserve_vcc 1
		.amdhsa_float_round_mode_32 0
		.amdhsa_float_round_mode_16_64 0
		.amdhsa_float_denorm_mode_32 3
		.amdhsa_float_denorm_mode_16_64 3
		.amdhsa_dx10_clamp 1
		.amdhsa_ieee_mode 1
		.amdhsa_fp16_overflow 0
		.amdhsa_tg_split 0
		.amdhsa_exception_fp_ieee_invalid_op 0
		.amdhsa_exception_fp_denorm_src 0
		.amdhsa_exception_fp_ieee_div_zero 0
		.amdhsa_exception_fp_ieee_overflow 0
		.amdhsa_exception_fp_ieee_underflow 0
		.amdhsa_exception_fp_ieee_inexact 0
		.amdhsa_exception_int_div_zero 0
	.end_amdhsa_kernel

; __global__ void __launch_bounds__(NTHREADS, 2) fwd_megakernel(Params p) {
amdhsa.kernels:
  - .agpr_count:     0
    .args:
      - .offset:         0
        .size:           160
        .value_kind:     by_value
      - .offset:         160
        .size:           4
        .value_kind:     hidden_block_count_x
      - .offset:         164
        .size:           4
        .value_kind:     hidden_block_count_y
      - .offset:         168
        .size:           4
        .value_kind:     hidden_block_count_z
      - .offset:         172
        .size:           2
        .value_kind:     hidden_group_size_x
      - .offset:         174
        .size:           2
        .value_kind:     hidden_group_size_y
      - .offset:         176
        .size:           2
        .value_kind:     hidden_group_size_z
      - .offset:         178
        .size:           2
        .value_kind:     hidden_remainder_x
      - .offset:         180
        .size:           2
        .value_kind:     hidden_remainder_y
      - .offset:         182
        .size:           2
        .value_kind:     hidden_remainder_z
      - .offset:         200
        .size:           8
        .value_kind:     hidden_global_offset_x
      - .offset:         208
        .size:           8
        .value_kind:     hidden_global_offset_y
      - .offset:         216
        .size:           8
        .value_kind:     hidden_global_offset_z
      - .offset:         224
        .size:           2
        .value_kind:     hidden_grid_dims
      - .offset:         248
        .size:           8
        .value_kind:     hidden_multigrid_sync_arg
      - .offset:         280
        .size:           4
        .value_kind:     hidden_dynamic_lds_size
    .group_segment_fixed_size: 0
    .kernarg_segment_align: 8
    .kernarg_segment_size: 416
    .language:       OpenCL C
    .language_version:
      - 2
      - 0
    .max_flat_workgroup_size: 512
    .name:           _Z14fwd_megakernel6Params
    .private_segment_fixed_size: 0
    .sgpr_count:     108
    .sgpr_spill_count: 155
    .symbol:         _Z14fwd_megakernel6Params.kd
    .uniform_work_group_size: 1
    .uses_dynamic_stack: false
    .vgpr_count:     251
    .vgpr_spill_count: 0
    .wavefront_size: 64
